# G1: trailing half's offset barrier deferred past next-unit index/pointer setup
# speedup vs baseline: 1.0047x; 1.0021x over previous
; __device__ __forceinline__ int fresh_tid() { int t = (int)threadIdx.x; asm volatile("" : "+v"(t)); return t; }
; #define PG8_STAGE(bufoff, gbase, voff) do { _Pragma("unroll") for (int _i = 0; _i < 2; ++_i) \
;         __builtin_amdgcn_global_load_lds((const unsigned*)((const char*)(gbase) + (voff)[_i]), (PG8_LAS unsigned*)(lds + (bufoff) + ldsw + _i * 8192), 16, 0, 0); } while (0)
; template <class Epi, class Sched, bool ALIGN_EPI = false, bool SP2 = false>
; __device__ __forceinline__ void gemm_phase(PG8_LAS unsigned char* lds, const Gemm g, const Sched& S, const Epi& E) {
;     const int tid = fresh_tid(), wid = __builtin_amdgcn_readfirstlane(tid >> 6), lane = tid & 63, wr = wid >> 2, wc = wid & 3, fr = lane & 15, fq = lane >> 4;
;     const int K = g.K, nt = K / BK;
;     unsigned voffA[2], voffB[2];
; #pragma unroll
;     for (int i = 0; i < 2; ++i) { int R, C; stage_rc(tid * 16 + i * 8192, R, C); const int Rb = Epi::PERM ? ((R & ~31) + perm32(R & 31)) : R;
;         voffA[i] = (unsigned)(R * K + C) * 2u; voffB[i] = (unsigned)(Rb * K + C) * 2u; }
;     const size_t kstep = (size_t)(BK * 2);
;     const size_t hstep = (size_t)HALF * K * 2;
;     const size_t tstep = 2 * hstep;
;     const unsigned ldsw = (unsigned)wid * 1024u;
;     const int aoff = lds_byte(wr * 64 + fr, fq * 8), boff = lds_byte(wc * 32 + fr, fq * 8);
;     ...
;     Unit cur, nxt; int ui = 0;
;     if (!S.next(0, cur)) return;
;     f32x4 acc[2][2][4][2];
; #pragma unroll
;     for (int a = 0; a < 2; ++a)
; #pragma unroll
;         for (int b = 0; b < 2; ++b)
; #pragma unroll
;             for (int m = 0; m < 4; ++m)
; #pragma unroll
;                 for (int n = 0; n < 2; ++n) acc[a][b][m][n] = (f32x4){0.f, 0.f, 0.f, 0.f};
;     bf16x8 At[4][2], B0[2][2], B1[2][2];
;     const char* cA = (const char*)g.A + (size_t)cur.pm * tstep; const char* cB = (const char*)g.Bt + (size_t)cur.pn * tstep;
;     S.a_ready(cur);
;     if constexpr (SP2) {
;         PG8_STAGE(PG8_SB(0, 0), cB, voffB); PG8_STAGE(PG8_SB(0, 1), cB + hstep, voffB); PG8_STAGE(PG8_SA(0, 0), cA, voffA); PG8_STAGE(PG8_SA(0, 1), cA + hstep, voffA);
;         if (wr == 1) PG8_BAR;
;         PG8_WAIT_V(2); PG8_BAR;
;         PG8_STAGE(PG8_SB(1, 0), cB + kstep, voffB); PG8_STAGE(PG8_SA(1, 0), cA + kstep, voffA); PG8_STAGE(PG8_SB(1, 1), cB + hstep + kstep, voffB);
;         PG8_WAIT_V(6); PG8_BAR;
.LBB0_192:
	s_add_u32 s10, s4, 0x12800000
	s_addc_u32 s11, s5, 0
	v_readlane_b32 s18, v255, 12
	s_add_u32 s4, s4, s18
	s_addc_u32 s5, s5, 0
	s_lshl_b32 s17, s17, 5
	s_and_b32 s23, s17, 0x60
	s_add_i32 m0, s52, 0x18000
	v_lshl_add_u64 v[6:7], v[6:7], 0, s[70:71]
	s_lshl_b32 s22, s16, 13
	s_lshl_b32 s17, s23, 7
	s_waitcnt vmcnt(2)
	s_barrier
	global_load_lds_dwordx4 v[6:7], off
	v_lshl_add_u64 v[4:5], v[4:5], 0, s[70:71]
	s_add_i32 m0, s52, 0x1a000
	s_add_i32 s56, s52, 0x8000
	s_add_i32 s57, s52, 0xa000
	global_load_lds_dwordx4 v[4:5], off
	v_lshl_add_u64 v[0:1], v[0:1], 0, s[70:71]
	s_mov_b32 m0, s56
	s_add_u32 s18, s44, 0x40080
	global_load_lds_dwordx4 v[0:1], off
	v_lshl_add_u64 v[0:1], v[2:3], 0, s[70:71]
	s_mov_b32 m0, s57
	s_addc_u32 s19, s45, 0
	global_load_lds_dwordx4 v[0:1], off
	s_add_i32 m0, s52, 0x1c000
	v_lshl_add_u64 v[0:1], s[18:19], 0, v[180:181]
	global_load_lds_dwordx4 v[0:1], off
	v_lshl_add_u64 v[0:1], s[18:19], 0, v[152:153]
	s_add_i32 m0, s52, 0x1e000
	v_bfe_u32 v2, v8, 4, 2
	global_load_lds_dwordx4 v[0:1], off
	v_and_b32_e32 v1, 15, v8
	v_lshlrev_b32_e32 v0, 4, v2
	v_lshlrev_b32_e32 v3, 2, v8
	v_lshl_or_b32 v190, s16, 6, v1
	v_lshl_or_b32 v1, v1, 6, v0
	v_and_b32_e32 v3, 32, v3
	v_bitop3_b32 v4, v1, s22, v3 bitop3:0xde
	v_bitop3_b32 v191, v1, s17, v3 bitop3:0xde
	v_mov_b32_e32 v1, v181
	v_lshl_add_u64 v[158:159], s[4:5], 0, v[0:1]
	v_lshlrev_b32_e32 v0, 14, v13
	v_and_b32_e32 v0, 0xffff8000, v0
	v_lshl_add_u32 v0, v12, 11, v0
	v_and_b32_e32 v1, 1, v13
	v_lshl_or_b32 v0, v1, 6, v0
	v_lshl_add_u32 v160, v14, 1, v0
	v_lshlrev_b32_e32 v0, 14, v9
	v_and_b32_e32 v0, 0xffff8000, v0
	s_waitcnt vmcnt(6)
	v_lshl_add_u32 v0, v10, 11, v0
	v_and_b32_e32 v1, 1, v9
	s_cmpk_lt_u32 s3, 0x100
	v_lshl_or_b32 v0, v1, 6, v0
	v_readlane_b32 s4, v254, 6
	s_cselect_b64 s[16:17], -1, 0
	v_lshl_or_b32 v192, v2, 3, s23
	v_mov_b32_e32 v161, v181
	v_lshl_add_u32 v162, v11, 1, v0
	v_mov_b32_e32 v163, v181
	s_mov_b32 s58, 0
	v_add_u32_e32 v193, 0, v4
	v_readlane_b32 s3, v254, 5
	s_mov_b32 s59, s4
	s_barrier
	v_readlane_b32 s5, v254, 7
	s_mov_b32 s96, 0
	s_branch .LBB0_195

; #define PG8_STAGE(bufoff, gbase, voff) do { _Pragma("unroll") for (int _i = 0; _i < 2; ++_i) \
;         __builtin_amdgcn_global_load_lds((const unsigned*)((const char*)(gbase) + (voff)[_i]), (PG8_LAS unsigned*)(lds + (bufoff) + ldsw + _i * 8192), 16, 0, 0); } while (0)
; #define PG8_LDA(dst, b, h) do { _Pragma("unroll") for (int m = 0; m < 4; ++m) _Pragma("unroll") for (int k = 0; k < 2; ++k) dst[m][k] = *(const PG8_LAS bf16x8*)(lds + PG8_SA(b, h) + aoff + m * 2048 + k * 1024); } while (0)
; #define PG8_LDB(dst, b, h) do { _Pragma("unroll") for (int n = 0; n < 2; ++n) _Pragma("unroll") for (int k = 0; k < 2; ++k) dst[n][k] = *(const PG8_LAS bf16x8*)(lds + PG8_SB(b, h) + boff + n * 2048 + k * 1024); } while (0)
; #define PG8_WAIT_V(n) asm volatile("s_waitcnt vmcnt(" #n ")" ::: "memory")
; #define PG8_WAIT_L(n) asm volatile("s_waitcnt lgkmcnt(" #n ")" ::: "memory")
; #define PG8_BAR __builtin_amdgcn_s_barrier()
; #define PG8_SCHED __builtin_amdgcn_sched_barrier(0)
; template <class Epi, class Sched, bool ALIGN_EPI = false, bool SP2 = false>
; __device__ __forceinline__ void gemm_phase(PG8_LAS unsigned char* lds, const Gemm g, const Sched& S, const Epi& E) {
;     ...
;         const bool has_next = S.next(ui + 1, nxt);
;         const char* nA = has_next ? (const char*)g.A + (size_t)nxt.pm * tstep : cA; const char* nB = has_next ? (const char*)g.Bt + (size_t)nxt.pn * tstep : cB;
;         for (int t = 0; t < nt; t += 2) {
;             const bool last = (t == nt - 2);
;             const char* a1 = cA + (size_t)(t + 1) * kstep;
;             const char* a2 = last ? nA : cA + (size_t)(t + 2) * kstep; const char* b2 = last ? nB : cB + (size_t)(t + 2) * kstep;
;             const char* a3 = a2 + kstep; const char* b3 = b2 + kstep;
;             if (last && has_next) S.a_ready(nxt);
;             if constexpr (SP2) {
;             PG8_LDB(B0, 0, 0); PG8_LDB(B1, 0, 1); PG8_SCHED; PG8_LDA(At, 0, 0); PG8_STAGE(PG8_SA(1, 1), a1 + hstep, voffA);
;             PG8_WAIT_V(8); PG8_WAIT_L(0); PG8_BAR; PG8_MMA(0, 0, At, B0); PG8_MMA(0, 1, At, B1); PG8_BAR; PG8_SCHED;
;             PG8_LDA(At, 0, 1); PG8_STAGE(PG8_SB(0, 0), b2, voffB); PG8_STAGE(PG8_SB(0, 1), b2 + hstep, voffB); PG8_STAGE(PG8_SA(0, 0), a2, voffA);
;             PG8_WAIT_V(8); PG8_WAIT_L(0); PG8_BAR; PG8_MMA(1, 0, At, B0); PG8_MMA(1, 1, At, B1); PG8_BAR; PG8_SCHED;
.LBB0_197:
	s_ashr_i32 s39, s38, 31
	s_lshl_b64 s[22:23], s[38:39], 19
	s_add_u32 s40, s13, s22
	s_addc_u32 s41, s36, s23
	s_and_b64 s[22:23], s[4:5], exec
	s_cselect_b32 s22, s41, s7
	s_cselect_b32 s23, s40, s6
	s_ashr_i32 s19, s18, 31
	s_lshl_b64 s[42:43], s[18:19], 19
	s_add_u32 s42, s37, s42
	s_addc_u32 s43, s46, s43
	s_and_b64 s[50:51], s[4:5], exec
	s_cselect_b32 s19, s43, s45
	s_cselect_b32 s39, s42, s44
	s_add_u32 s6, s6, 0x40080
	s_addc_u32 s7, s7, 0
	s_add_u32 s60, s44, 0x100
	s_addc_u32 s61, s45, 0
	s_mov_b32 s62, -2
	s_cmp_eq_u32 s96, 0
	s_cbranch_scc1 .Lg1_noe2
	s_barrier
	s_mov_b32 s96, 0
.Lg1_noe2:
	s_add_u32 s44, s6, 0xfffc0080
	s_addc_u32 s45, s7, -1
	s_add_i32 s63, 0, 0x10000
	s_cmp_eq_u32 s62, 12
	s_cselect_b32 s51, s22, s45
	s_cselect_b32 s50, s23, s44
	s_cselect_b32 s45, s19, s61
	s_cselect_b32 s44, s39, s60
	s_add_i32 s73, 0, 0x14000
	v_add_u32_e32 v140, s63, v191
	v_add_u32_e32 v168, s73, v191
	ds_read_b128 v[128:131], v140
	ds_read_b128 v[132:135], v140 offset:1024
	ds_read_b128 v[136:139], v140 offset:2048
	ds_read_b128 v[140:143], v140 offset:3072
	ds_read_b128 v[144:147], v168
	ds_read_b128 v[148:151], v168 offset:1024
	ds_read_b128 v[164:167], v168 offset:2048
	ds_read_b128 v[168:171], v168 offset:3072
	v_lshl_add_u64 v[202:203], s[6:7], 0, v[160:161]
	s_add_i32 m0, s52, 0xc000
	ds_read_b128 v[172:175], v193
	ds_read_b128 v[176:179], v193 offset:1024
	ds_read_b128 v[186:189], v193 offset:2048
	ds_read_b128 v[194:197], v193 offset:3072
	ds_read_b128 v[198:201], v193 offset:4096
	ds_read_b128 v[216:219], v193 offset:5120
	ds_read_b128 v[224:227], v193 offset:6144
	ds_read_b128 v[230:233], v193 offset:7168
	global_load_lds_dwordx4 v[202:203], off
	v_lshl_add_u64 v[202:203], s[6:7], 0, v[162:163]
	s_add_i32 m0, s52, 0xe000
	s_nop 0
	global_load_lds_dwordx4 v[202:203], off
	s_waitcnt vmcnt(8)
	s_waitcnt lgkmcnt(0)
	s_setprio 1
	s_barrier
	v_mfma_f32_16x16x32_bf16 v[124:127], v[128:131], v[172:175], 0
	v_mfma_f32_16x16x32_bf16 v[112:115], v[136:139], v[172:175], 0
	v_mfma_f32_16x16x32_bf16 v[108:111], v[128:131], v[186:189], 0
	v_mfma_f32_16x16x32_bf16 v[96:99], v[136:139], v[186:189], 0
	v_mfma_f32_16x16x32_bf16 v[92:95], v[128:131], v[198:201], 0
	v_mfma_f32_16x16x32_bf16 v[80:83], v[136:139], v[198:201], 0
	v_mfma_f32_16x16x32_bf16 v[76:79], v[128:131], v[224:227], 0
	v_mfma_f32_16x16x32_bf16 v[64:67], v[136:139], v[224:227], 0
	v_mfma_f32_16x16x32_bf16 v[124:127], v[132:135], v[176:179], v[124:127]
	v_mfma_f32_16x16x32_bf16 v[112:115], v[140:143], v[176:179], v[112:115]
	v_mfma_f32_16x16x32_bf16 v[108:111], v[132:135], v[194:197], v[108:111]
	v_mfma_f32_16x16x32_bf16 v[96:99], v[140:143], v[194:197], v[96:99]
	v_mfma_f32_16x16x32_bf16 v[92:95], v[132:135], v[216:219], v[92:95]
	v_mfma_f32_16x16x32_bf16 v[80:83], v[140:143], v[216:219], v[80:83]
	v_mfma_f32_16x16x32_bf16 v[76:79], v[132:135], v[230:233], v[76:79]
	v_mfma_f32_16x16x32_bf16 v[64:67], v[140:143], v[230:233], v[64:67]
	s_setprio 0
	s_setprio 1
	v_mfma_f32_16x16x32_bf16 v[120:123], v[144:147], v[172:175], 0
	v_mfma_f32_16x16x32_bf16 v[116:119], v[164:167], v[172:175], 0
	v_mfma_f32_16x16x32_bf16 v[104:107], v[144:147], v[186:189], 0
	v_mfma_f32_16x16x32_bf16 v[100:103], v[164:167], v[186:189], 0
	v_mfma_f32_16x16x32_bf16 v[88:91], v[144:147], v[198:201], 0
	v_mfma_f32_16x16x32_bf16 v[84:87], v[164:167], v[198:201], 0
	v_mfma_f32_16x16x32_bf16 v[72:75], v[144:147], v[224:227], 0
	v_mfma_f32_16x16x32_bf16 v[68:71], v[164:167], v[224:227], 0
	v_mfma_f32_16x16x32_bf16 v[120:123], v[148:151], v[176:179], v[120:123]
	v_mfma_f32_16x16x32_bf16 v[116:119], v[168:171], v[176:179], v[116:119]
	v_mfma_f32_16x16x32_bf16 v[104:107], v[148:151], v[194:197], v[104:107]
	v_mfma_f32_16x16x32_bf16 v[100:103], v[168:171], v[194:197], v[100:103]
	v_mfma_f32_16x16x32_bf16 v[88:91], v[148:151], v[216:219], v[88:91]
	v_mfma_f32_16x16x32_bf16 v[84:87], v[168:171], v[216:219], v[84:87]
	v_mfma_f32_16x16x32_bf16 v[72:75], v[148:151], v[230:233], v[72:75]
	v_mfma_f32_16x16x32_bf16 v[68:71], v[168:171], v[230:233], v[68:71]
	s_barrier
	s_setprio 0
	s_add_i32 s63, s63, s47
	v_lshl_add_u64 v[202:203], s[44:45], 0, v[180:181]
	s_mov_b32 m0, s63
	ds_read_b128 v[172:175], v193 offset:16384
	ds_read_b128 v[176:179], v193 offset:17408
	ds_read_b128 v[186:189], v193 offset:18432
	ds_read_b128 v[194:197], v193 offset:19456
	ds_read_b128 v[198:201], v193 offset:20480
	ds_read_b128 v[216:219], v193 offset:21504
	ds_read_b128 v[224:227], v193 offset:22528
	ds_read_b128 v[230:233], v193 offset:23552
	global_load_lds_dwordx4 v[202:203], off
	s_add_i32 m0, s63, 0x2000
	s_add_u32 s76, s44, 0x40000
	v_lshl_add_u64 v[208:209], s[44:45], 0, v[152:153]
	s_addc_u32 s77, s45, 0
	s_add_i32 s63, s73, s47
	global_load_lds_dwordx4 v[208:209], off
	v_lshl_add_u64 v[220:221], s[76:77], 0, v[180:181]
	s_mov_b32 m0, s63
	v_lshl_add_u64 v[234:235], s[50:51], 0, v[154:155]
	global_load_lds_dwordx4 v[220:221], off
	v_lshl_add_u64 v[220:221], s[76:77], 0, v[152:153]
	s_add_i32 m0, s63, 0x2000
	s_nop 0
	global_load_lds_dwordx4 v[220:221], off
	v_lshl_add_u64 v[220:221], s[50:51], 0, v[156:157]
	s_mov_b32 m0, s52
	s_nop 0
	global_load_lds_dwordx4 v[220:221], off
	s_mov_b32 m0, s53
	s_nop 0
	global_load_lds_dwordx4 v[234:235], off
	s_waitcnt vmcnt(8)
	s_waitcnt lgkmcnt(0)
	s_setprio 1
	s_barrier
; #define PG8_STAGE(bufoff, gbase, voff) do { _Pragma("unroll") for (int _i = 0; _i < 2; ++_i) \
;         __builtin_amdgcn_global_load_lds((const unsigned*)((const char*)(gbase) + (voff)[_i]), (PG8_LAS unsigned*)(lds + (bufoff) + ldsw + _i * 8192), 16, 0, 0); } while (0)
; #define PG8_LDA(dst, b, h) do { _Pragma("unroll") for (int m = 0; m < 4; ++m) _Pragma("unroll") for (int k = 0; k < 2; ++k) dst[m][k] = *(const PG8_LAS bf16x8*)(lds + PG8_SA(b, h) + aoff + m * 2048 + k * 1024); } while (0)
; #define PG8_LDB(dst, b, h) do { _Pragma("unroll") for (int n = 0; n < 2; ++n) _Pragma("unroll") for (int k = 0; k < 2; ++k) dst[n][k] = *(const PG8_LAS bf16x8*)(lds + PG8_SB(b, h) + boff + n * 2048 + k * 1024); } while (0)
; #define PG8_MMA(ai, bj, At, Bt) do { __builtin_amdgcn_s_setprio(1); _Pragma("unroll") for (int m = 0; m < 4; ++m) _Pragma("unroll") for (int n = 0; n < 2; ++n) _Pragma("unroll") for (int k = 0; k < 2; ++k) \
;         acc[ai][bj][m][n] = __builtin_amdgcn_mfma_f32_16x16x32_bf16(Bt[n][k], At[m][k], acc[ai][bj][m][n], 0, 0, 0); __builtin_amdgcn_s_setprio(0); } while (0)
; #define PG8_WAIT_V(n) asm volatile("s_waitcnt vmcnt(" #n ")" ::: "memory")
; #define PG8_WAIT_L(n) asm volatile("s_waitcnt lgkmcnt(" #n ")" ::: "memory")
; #define PG8_BAR __builtin_amdgcn_s_barrier()
; #define PG8_SCHED __builtin_amdgcn_sched_barrier(0)
; template <class Epi, class Sched, bool ALIGN_EPI = false, bool SP2 = false>
; __device__ __forceinline__ void gemm_phase(PG8_LAS unsigned char* lds, const Gemm g, const Sched& S, const Epi& E) {
;     ...
;             PG8_WAIT_V(8); PG8_WAIT_L(0); PG8_BAR; PG8_MMA(0, 0, At, B0); PG8_MMA(0, 1, At, B1); PG8_BAR; PG8_SCHED;
;             PG8_LDA(At, 0, 1); PG8_STAGE(PG8_SB(0, 0), b2, voffB); PG8_STAGE(PG8_SB(0, 1), b2 + hstep, voffB); PG8_STAGE(PG8_SA(0, 0), a2, voffA);
;             PG8_WAIT_V(8); PG8_WAIT_L(0); PG8_BAR; PG8_MMA(1, 0, At, B0); PG8_MMA(1, 1, At, B1); PG8_BAR; PG8_SCHED;
;             PG8_LDB(B0, 1, 0); PG8_LDB(B1, 1, 1); PG8_SCHED; PG8_LDA(At, 1, 0); PG8_STAGE(PG8_SA(0, 1), a2 + hstep, voffA);
;             PG8_WAIT_V(8); PG8_WAIT_L(0); PG8_BAR; PG8_MMA(0, 0, At, B0); PG8_MMA(0, 1, At, B1); PG8_BAR; PG8_SCHED;
	v_mfma_f32_16x16x32_bf16 v[60:63], v[128:131], v[172:175], 0
	v_mfma_f32_16x16x32_bf16 v[48:51], v[136:139], v[172:175], 0
	v_mfma_f32_16x16x32_bf16 v[44:47], v[128:131], v[186:189], 0
	v_mfma_f32_16x16x32_bf16 v[32:35], v[136:139], v[186:189], 0
	v_mfma_f32_16x16x32_bf16 v[28:31], v[128:131], v[198:201], 0
	v_mfma_f32_16x16x32_bf16 v[16:19], v[136:139], v[198:201], 0
	v_mfma_f32_16x16x32_bf16 v[12:15], v[128:131], v[224:227], 0
	v_mfma_f32_16x16x32_bf16 v[4:7], v[136:139], v[224:227], 0
	v_mfma_f32_16x16x32_bf16 v[60:63], v[132:135], v[176:179], v[60:63]
	v_mfma_f32_16x16x32_bf16 v[48:51], v[140:143], v[176:179], v[48:51]
	v_mfma_f32_16x16x32_bf16 v[44:47], v[132:135], v[194:197], v[44:47]
	v_mfma_f32_16x16x32_bf16 v[32:35], v[140:143], v[194:197], v[32:35]
	v_mfma_f32_16x16x32_bf16 v[28:31], v[132:135], v[216:219], v[28:31]
	v_mfma_f32_16x16x32_bf16 v[16:19], v[140:143], v[216:219], v[16:19]
	v_mfma_f32_16x16x32_bf16 v[12:15], v[132:135], v[230:233], v[12:15]
	v_mfma_f32_16x16x32_bf16 v[4:7], v[140:143], v[230:233], v[4:7]
	s_setprio 0
	s_setprio 1
	v_mfma_f32_16x16x32_bf16 v[56:59], v[144:147], v[172:175], 0
	v_mfma_f32_16x16x32_bf16 v[52:55], v[164:167], v[172:175], 0
	v_mfma_f32_16x16x32_bf16 v[40:43], v[144:147], v[186:189], 0
	v_mfma_f32_16x16x32_bf16 v[36:39], v[164:167], v[186:189], 0
	v_mfma_f32_16x16x32_bf16 v[24:27], v[144:147], v[198:201], 0
	v_mfma_f32_16x16x32_bf16 v[20:23], v[164:167], v[198:201], 0
	v_mfma_f32_16x16x32_bf16 v[8:11], v[144:147], v[224:227], 0
	v_mfma_f32_16x16x32_bf16 v[0:3], v[164:167], v[224:227], 0
	v_mfma_f32_16x16x32_bf16 v[56:59], v[148:151], v[176:179], v[56:59]
	v_mfma_f32_16x16x32_bf16 v[52:55], v[168:171], v[176:179], v[52:55]
	v_mfma_f32_16x16x32_bf16 v[40:43], v[148:151], v[194:197], v[40:43]
	v_mfma_f32_16x16x32_bf16 v[36:39], v[168:171], v[194:197], v[36:39]
	v_mfma_f32_16x16x32_bf16 v[24:27], v[148:151], v[216:219], v[24:27]
	v_mfma_f32_16x16x32_bf16 v[20:23], v[168:171], v[216:219], v[20:23]
	v_mfma_f32_16x16x32_bf16 v[8:11], v[148:151], v[230:233], v[8:11]
	v_mfma_f32_16x16x32_bf16 v[0:3], v[168:171], v[230:233], v[0:3]
	s_barrier
	s_setprio 0
	s_add_i32 s63, 0, 0x18000
	s_add_i32 s73, 0, 0x1c000
	v_add_u32_e32 v140, s63, v191
	v_add_u32_e32 v168, s73, v191
	ds_read_b128 v[128:131], v140
	ds_read_b128 v[132:135], v140 offset:1024
	ds_read_b128 v[136:139], v140 offset:2048
	ds_read_b128 v[140:143], v140 offset:3072
	ds_read_b128 v[144:147], v168
	ds_read_b128 v[148:151], v168 offset:1024
	ds_read_b128 v[164:167], v168 offset:2048
	ds_read_b128 v[168:171], v168 offset:3072
	s_add_u32 s50, s50, 0x40000
	s_addc_u32 s51, s51, 0
	s_mov_b32 m0, s54
	v_lshl_add_u64 v[236:237], s[50:51], 0, v[156:157]
	ds_read_b128 v[172:175], v193 offset:32768
	ds_read_b128 v[176:179], v193 offset:33792
	ds_read_b128 v[186:189], v193 offset:34816
	ds_read_b128 v[194:197], v193 offset:35840
	ds_read_b128 v[198:201], v193 offset:36864
	ds_read_b128 v[216:219], v193 offset:37888
	ds_read_b128 v[224:227], v193 offset:38912
	ds_read_b128 v[230:233], v193 offset:39936
	global_load_lds_dwordx4 v[236:237], off
	v_lshl_add_u64 v[236:237], s[50:51], 0, v[154:155]
	s_mov_b32 m0, s55
	s_nop 0
	global_load_lds_dwordx4 v[236:237], off
	s_waitcnt vmcnt(8)
	s_waitcnt lgkmcnt(0)
	s_setprio 1
	s_barrier
	v_mfma_f32_16x16x32_bf16 v[124:127], v[128:131], v[172:175], v[124:127]
	v_mfma_f32_16x16x32_bf16 v[112:115], v[136:139], v[172:175], v[112:115]
	v_mfma_f32_16x16x32_bf16 v[108:111], v[128:131], v[186:189], v[108:111]
	v_mfma_f32_16x16x32_bf16 v[96:99], v[136:139], v[186:189], v[96:99]
	v_mfma_f32_16x16x32_bf16 v[92:95], v[128:131], v[198:201], v[92:95]
	v_mfma_f32_16x16x32_bf16 v[80:83], v[136:139], v[198:201], v[80:83]
	v_mfma_f32_16x16x32_bf16 v[76:79], v[128:131], v[224:227], v[76:79]
	v_mfma_f32_16x16x32_bf16 v[64:67], v[136:139], v[224:227], v[64:67]
	v_mfma_f32_16x16x32_bf16 v[124:127], v[132:135], v[176:179], v[124:127]
	v_mfma_f32_16x16x32_bf16 v[112:115], v[140:143], v[176:179], v[112:115]
	v_mfma_f32_16x16x32_bf16 v[108:111], v[132:135], v[194:197], v[108:111]
	v_mfma_f32_16x16x32_bf16 v[96:99], v[140:143], v[194:197], v[96:99]
	v_mfma_f32_16x16x32_bf16 v[92:95], v[132:135], v[216:219], v[92:95]
	v_mfma_f32_16x16x32_bf16 v[80:83], v[140:143], v[216:219], v[80:83]
	v_mfma_f32_16x16x32_bf16 v[76:79], v[132:135], v[230:233], v[76:79]
	v_mfma_f32_16x16x32_bf16 v[64:67], v[140:143], v[230:233], v[64:67]
	s_setprio 0
	s_setprio 1
	v_mfma_f32_16x16x32_bf16 v[120:123], v[144:147], v[172:175], v[120:123]
	v_mfma_f32_16x16x32_bf16 v[116:119], v[164:167], v[172:175], v[116:119]
	v_mfma_f32_16x16x32_bf16 v[104:107], v[144:147], v[186:189], v[104:107]
	v_mfma_f32_16x16x32_bf16 v[100:103], v[164:167], v[186:189], v[100:103]
	v_mfma_f32_16x16x32_bf16 v[88:91], v[144:147], v[198:201], v[88:91]
	v_mfma_f32_16x16x32_bf16 v[84:87], v[164:167], v[198:201], v[84:87]
	v_mfma_f32_16x16x32_bf16 v[72:75], v[144:147], v[224:227], v[72:75]
	v_mfma_f32_16x16x32_bf16 v[68:71], v[164:167], v[224:227], v[68:71]
	v_mfma_f32_16x16x32_bf16 v[120:123], v[148:151], v[176:179], v[120:123]
	v_mfma_f32_16x16x32_bf16 v[116:119], v[168:171], v[176:179], v[116:119]
	v_mfma_f32_16x16x32_bf16 v[104:107], v[148:151], v[194:197], v[104:107]
	v_mfma_f32_16x16x32_bf16 v[100:103], v[168:171], v[194:197], v[100:103]
	v_mfma_f32_16x16x32_bf16 v[88:91], v[148:151], v[216:219], v[88:91]
	v_mfma_f32_16x16x32_bf16 v[84:87], v[168:171], v[216:219], v[84:87]
	v_mfma_f32_16x16x32_bf16 v[72:75], v[148:151], v[230:233], v[72:75]
	v_mfma_f32_16x16x32_bf16 v[68:71], v[168:171], v[230:233], v[68:71]
	s_barrier
; #define PG8_STAGE(bufoff, gbase, voff) do { _Pragma("unroll") for (int _i = 0; _i < 2; ++_i) \
;         __builtin_amdgcn_global_load_lds((const unsigned*)((const char*)(gbase) + (voff)[_i]), (PG8_LAS unsigned*)(lds + (bufoff) + ldsw + _i * 8192), 16, 0, 0); } while (0)
; #define PG8_LDA(dst, b, h) do { _Pragma("unroll") for (int m = 0; m < 4; ++m) _Pragma("unroll") for (int k = 0; k < 2; ++k) dst[m][k] = *(const PG8_LAS bf16x8*)(lds + PG8_SA(b, h) + aoff + m * 2048 + k * 1024); } while (0)
; #define PG8_MMA(ai, bj, At, Bt) do { __builtin_amdgcn_s_setprio(1); _Pragma("unroll") for (int m = 0; m < 4; ++m) _Pragma("unroll") for (int n = 0; n < 2; ++n) _Pragma("unroll") for (int k = 0; k < 2; ++k) \
;         acc[ai][bj][m][n] = __builtin_amdgcn_mfma_f32_16x16x32_bf16(Bt[n][k], At[m][k], acc[ai][bj][m][n], 0, 0, 0); __builtin_amdgcn_s_setprio(0); } while (0)
; #define PG8_WAIT_V(n) asm volatile("s_waitcnt vmcnt(" #n ")" ::: "memory")
; #define PG8_WAIT_L(n) asm volatile("s_waitcnt lgkmcnt(" #n ")" ::: "memory")
; #define PG8_BAR __builtin_amdgcn_s_barrier()
; #define PG8_SCHED __builtin_amdgcn_sched_barrier(0)
; template <class Epi, class Sched, bool ALIGN_EPI = false, bool SP2 = false>
; __device__ __forceinline__ void gemm_phase(PG8_LAS unsigned char* lds, const Gemm g, const Sched& S, const Epi& E) {
;     ...
;             PG8_WAIT_V(8); PG8_WAIT_L(0); PG8_BAR; PG8_MMA(0, 0, At, B0); PG8_MMA(0, 1, At, B1); PG8_BAR; PG8_SCHED;
;             PG8_LDA(At, 1, 1); PG8_STAGE(PG8_SB(1, 0), b3, voffB); PG8_STAGE(PG8_SB(1, 1), b3 + hstep, voffB); PG8_STAGE(PG8_SA(1, 0), a3, voffA);
;             PG8_WAIT_V(8); PG8_WAIT_L(0); PG8_BAR; PG8_MMA(1, 0, At, B0); PG8_MMA(1, 1, At, B1); PG8_BAR; PG8_SCHED;
	s_setprio 0
	s_add_i32 s50, s63, s47
	v_lshl_add_u64 v[202:203], v[202:203], 0, s[70:71]
	s_mov_b32 m0, s50
	ds_read_b128 v[172:175], v193 offset:49152
	ds_read_b128 v[176:179], v193 offset:50176
	ds_read_b128 v[186:189], v193 offset:51200
	ds_read_b128 v[194:197], v193 offset:52224
	ds_read_b128 v[198:201], v193 offset:53248
	ds_read_b128 v[216:219], v193 offset:54272
	ds_read_b128 v[224:227], v193 offset:55296
	ds_read_b128 v[230:233], v193 offset:56320
	global_load_lds_dwordx4 v[202:203], off
	s_add_i32 m0, s50, 0x2000
	s_add_u32 s44, s44, 0x40080
	v_lshl_add_u64 v[202:203], v[208:209], 0, s[70:71]
	s_addc_u32 s45, s45, 0
	s_add_i32 s50, s73, s47
	global_load_lds_dwordx4 v[202:203], off
	v_lshl_add_u64 v[202:203], s[44:45], 0, v[180:181]
	s_mov_b32 m0, s50
	s_nop 0
	global_load_lds_dwordx4 v[202:203], off
	v_lshl_add_u64 v[202:203], s[44:45], 0, v[152:153]
	s_add_i32 m0, s50, 0x2000
	s_nop 0
	global_load_lds_dwordx4 v[202:203], off
	v_lshl_add_u64 v[202:203], v[220:221], 0, s[70:71]
	s_mov_b32 m0, s56
	s_nop 0
	global_load_lds_dwordx4 v[202:203], off
	v_lshl_add_u64 v[202:203], v[234:235], 0, s[70:71]
	s_mov_b32 m0, s57
	s_nop 0
	global_load_lds_dwordx4 v[202:203], off
	s_waitcnt vmcnt(8)
	s_waitcnt lgkmcnt(0)
	s_setprio 1
	s_barrier
	v_mfma_f32_16x16x32_bf16 v[60:63], v[128:131], v[172:175], v[60:63]
	v_mfma_f32_16x16x32_bf16 v[48:51], v[136:139], v[172:175], v[48:51]
	v_mfma_f32_16x16x32_bf16 v[44:47], v[128:131], v[186:189], v[44:47]
	v_mfma_f32_16x16x32_bf16 v[32:35], v[136:139], v[186:189], v[32:35]
	v_mfma_f32_16x16x32_bf16 v[28:31], v[128:131], v[198:201], v[28:31]
	v_mfma_f32_16x16x32_bf16 v[16:19], v[136:139], v[198:201], v[16:19]
	v_mfma_f32_16x16x32_bf16 v[12:15], v[128:131], v[224:227], v[12:15]
	v_mfma_f32_16x16x32_bf16 v[4:7], v[136:139], v[224:227], v[4:7]
	v_mfma_f32_16x16x32_bf16 v[60:63], v[132:135], v[176:179], v[60:63]
	v_mfma_f32_16x16x32_bf16 v[48:51], v[140:143], v[176:179], v[48:51]
	v_mfma_f32_16x16x32_bf16 v[44:47], v[132:135], v[194:197], v[44:47]
	v_mfma_f32_16x16x32_bf16 v[32:35], v[140:143], v[194:197], v[32:35]
	v_mfma_f32_16x16x32_bf16 v[28:31], v[132:135], v[216:219], v[28:31]
	v_mfma_f32_16x16x32_bf16 v[16:19], v[140:143], v[216:219], v[16:19]
	v_mfma_f32_16x16x32_bf16 v[12:15], v[132:135], v[230:233], v[12:15]
	v_mfma_f32_16x16x32_bf16 v[4:7], v[140:143], v[230:233], v[4:7]
	s_setprio 0
	s_setprio 1
	v_mfma_f32_16x16x32_bf16 v[56:59], v[144:147], v[172:175], v[56:59]
	v_mfma_f32_16x16x32_bf16 v[52:55], v[164:167], v[172:175], v[52:55]
	v_mfma_f32_16x16x32_bf16 v[40:43], v[144:147], v[186:189], v[40:43]
	v_mfma_f32_16x16x32_bf16 v[36:39], v[164:167], v[186:189], v[36:39]
	v_mfma_f32_16x16x32_bf16 v[24:27], v[144:147], v[198:201], v[24:27]
	v_mfma_f32_16x16x32_bf16 v[20:23], v[164:167], v[198:201], v[20:23]
	v_mfma_f32_16x16x32_bf16 v[8:11], v[144:147], v[224:227], v[8:11]
	v_mfma_f32_16x16x32_bf16 v[0:3], v[164:167], v[224:227], v[0:3]
	v_mfma_f32_16x16x32_bf16 v[56:59], v[148:151], v[176:179], v[56:59]
	v_mfma_f32_16x16x32_bf16 v[52:55], v[168:171], v[176:179], v[52:55]
	v_mfma_f32_16x16x32_bf16 v[40:43], v[148:151], v[194:197], v[40:43]
	v_mfma_f32_16x16x32_bf16 v[36:39], v[168:171], v[194:197], v[36:39]
	v_mfma_f32_16x16x32_bf16 v[24:27], v[148:151], v[216:219], v[24:27]
	v_mfma_f32_16x16x32_bf16 v[20:23], v[168:171], v[216:219], v[20:23]
	v_mfma_f32_16x16x32_bf16 v[8:11], v[148:151], v[230:233], v[8:11]
	v_mfma_f32_16x16x32_bf16 v[0:3], v[168:171], v[230:233], v[0:3]
	s_barrier
	s_setprio 0
	s_add_i32 s62, s62, 2
	s_add_u32 s6, s6, 0x100
	s_addc_u32 s7, s7, 0
	s_add_u32 s60, s60, 0x100
	s_addc_u32 s61, s61, 0
	s_cmp_gt_u32 s62, 13

; __device__ __forceinline__ unsigned cvt_pk_bf16(float lo, float hi) { unsigned r; asm volatile("v_cvt_pk_bf16_f32 %0, %1, %2" : "=v"(r) : "v"(lo), "v"(hi)); return r; }
;     __device__ __forceinline__ void operator()(const f32x4 (&acc)[2][2][4][2], const Unit& u, int wr, int wc, int fr, int fq) const {
;         const int row0 = u.pm * BM + wr * 64 + fr, col0 = u.pn * HALF + wc * 32 + 8 * fq;
;         float rsv[2][4]; row_rs8(rsv, part, row0, fq);
; #pragma unroll
;         for (int ai = 0; ai < 2; ++ai)
; #pragma unroll
;             for (int m = 0; m < 4; ++m) { const int row = row0 + ai * HALF + m * 16; const float rs = rsv[ai][m], c1 = rs * -1.4426950408889634f, rs2 = rs * rs;
;                 u32x4 w;
; #pragma unroll
;                 for (int n = 0; n < 2; ++n)
; #pragma unroll
;                     for (int h = 0; h < 2; ++h) { const f32x2 g = (f32x2){acc[ai][0][m][n][2 * h], acc[ai][0][m][n][2 * h + 1]}, up = (f32x2){acc[ai][1][m][n][2 * h], acc[ai][1][m][n][2 * h + 1]};
;                         const f32x2 t = g * c1; f32x2 d = (f32x2){__builtin_amdgcn_exp2f(t[0]), __builtin_amdgcn_exp2f(t[1])} + 1.0f;
;                         const f32x2 r = (f32x2){__builtin_amdgcn_rcpf(d[0]), __builtin_amdgcn_rcpf(d[1])}; const f32x2 o = (g * up) * (r * rs2);
;                         w[2 * n + h] = cvt_pk_bf16(o[0], o[1]); }
;                 __builtin_nontemporal_store(w, (u32x4*)(H + (size_t)row * ldh + col0)); }
.LBB0_201:
	v_lshl_add_u32 v178, s59, 8, v190
	v_lshlrev_b32_e32 v194, 2, v190
	v_add_u32_e32 v194, 0x20000, v194
	ds_read_b32 v171, v194
	ds_read_b32 v165, v194 offset:64
	ds_read_b32 v145, v194 offset:128
	ds_read_b32 v144, v194 offset:192
	ds_read_b32 v137, v194 offset:512
	ds_read_b32 v136, v194 offset:576
	ds_read_b32 v129, v194 offset:640
	ds_read_b32 v128, v194 offset:704
	v_or_b32_e32 v176, 16, v178
	v_or_b32_e32 v174, 32, v178
	v_or_b32_e32 v172, 48, v178
	v_add_u32_e32 v170, 0x80, v178
	v_add_u32_e32 v168, 0x90, v178
	v_add_u32_e32 v166, 0xa0, v178
	v_add_u32_e32 v164, 0xb0, v178
	v_lshl_or_b32 v186, s3, 7, v192
	v_ashrrev_i32_e32 v187, 31, v186
	v_pk_mul_f32 v[120:121], v[124:125], v[120:121]
	v_pk_mul_f32 v[122:123], v[126:127], v[122:123]
	v_pk_mul_f32 v[118:119], v[114:115], v[118:119]
	v_pk_mul_f32 v[104:105], v[108:109], v[104:105]
	v_pk_mul_f32 v[106:107], v[110:111], v[106:107]
	v_pk_mul_f32 v[102:103], v[98:99], v[102:103]
	v_pk_mul_f32 v[88:89], v[92:93], v[88:89]
	v_pk_mul_f32 v[90:91], v[94:95], v[90:91]
	v_pk_mul_f32 v[86:87], v[82:83], v[86:87]
	v_pk_mul_f32 v[72:73], v[76:77], v[72:73]
	v_pk_mul_f32 v[74:75], v[78:79], v[74:75]
	v_pk_mul_f32 v[70:71], v[66:67], v[70:71]
	v_pk_mul_f32 v[56:57], v[60:61], v[56:57]
	v_pk_mul_f32 v[58:59], v[62:63], v[58:59]
	v_pk_mul_f32 v[54:55], v[50:51], v[54:55]
	v_pk_mul_f32 v[40:41], v[44:45], v[40:41]
	v_pk_mul_f32 v[42:43], v[46:47], v[42:43]
	v_pk_mul_f32 v[38:39], v[34:35], v[38:39]
	v_pk_mul_f32 v[24:25], v[28:29], v[24:25]
	v_pk_mul_f32 v[26:27], v[30:31], v[26:27]
	v_pk_mul_f32 v[22:23], v[18:19], v[22:23]
	v_pk_mul_f32 v[8:9], v[12:13], v[8:9]
	v_pk_mul_f32 v[10:11], v[14:15], v[10:11]
	v_pk_mul_f32 v[0:1], v[4:5], v[0:1]
	v_pk_mul_f32 v[2:3], v[6:7], v[2:3]
	s_waitcnt lgkmcnt(0)
	s_andn2_b64 vcc, exec, s[4:5]
	v_mov_b64_e32 v[224:225], s[10:11]
	v_lshlrev_b64 v[226:227], 1, v[186:187]
	v_mul_f32_e32 v216, 0xbfb8aa3b, v171
	v_mul_f32_e32 v218, v171, v171
	v_pk_mul_f32 v[194:195], v[124:125], v[216:217] op_sel_hi:[1,0]
	v_pk_mul_f32 v[196:197], v[126:127], v[216:217] op_sel_hi:[1,0]
	v_pk_mul_f32 v[198:199], v[112:113], v[216:217] op_sel_hi:[1,0]
	v_pk_mul_f32 v[200:201], v[114:115], v[216:217] op_sel_hi:[1,0]
	v_pk_mul_f32 v[116:117], v[112:113], v[116:117]
	v_exp_f32_e32 v194, v194
	v_exp_f32_e32 v195, v195
	v_exp_f32_e32 v196, v196
	v_exp_f32_e32 v197, v197
	v_exp_f32_e32 v198, v198
	v_exp_f32_e32 v199, v199
	v_exp_f32_e32 v200, v200
	v_exp_f32_e32 v201, v201
	v_pk_add_f32 v[194:195], v[194:195], 1.0 op_sel_hi:[1,0]
	v_pk_add_f32 v[196:197], v[196:197], 1.0 op_sel_hi:[1,0]
	v_pk_add_f32 v[198:199], v[198:199], 1.0 op_sel_hi:[1,0]
	v_pk_add_f32 v[200:201], v[200:201], 1.0 op_sel_hi:[1,0]
	v_rcp_f32_e32 v194, v194
	v_rcp_f32_e32 v195, v195
	v_rcp_f32_e32 v196, v196
	v_rcp_f32_e32 v197, v197
	v_rcp_f32_e32 v198, v198
	v_rcp_f32_e32 v199, v199
	v_rcp_f32_e32 v200, v200
	v_rcp_f32_e32 v201, v201
	v_pk_mul_f32 v[194:195], v[218:219], v[194:195] op_sel_hi:[0,1]
	v_pk_mul_f32 v[196:197], v[218:219], v[196:197] op_sel_hi:[0,1]
	v_pk_mul_f32 v[198:199], v[218:219], v[198:199] op_sel_hi:[0,1]
	v_pk_mul_f32 v[200:201], v[218:219], v[200:201] op_sel_hi:[0,1]
	v_pk_mul_f32 v[120:121], v[120:121], v[194:195]
	v_pk_mul_f32 v[122:123], v[122:123], v[196:197]
	v_pk_mul_f32 v[116:117], v[116:117], v[198:199]
	v_pk_mul_f32 v[118:119], v[118:119], v[200:201]
	v_mad_i64_i32 v[230:231], s[6:7], v178, s25, v[224:225]
	v_cvt_pk_bf16_f32 v120, v120, v121
	v_cvt_pk_bf16_f32 v121, v122, v123
	v_cvt_pk_bf16_f32 v122, v116, v117
	v_cvt_pk_bf16_f32 v123, v118, v119
	v_lshl_add_u64 v[230:231], v[230:231], 0, v[226:227]
	global_store_dwordx4 v[230:231], v[120:123], off nt
	v_mul_f32_e32 v216, 0xbfb8aa3b, v165
	v_mul_f32_e32 v218, v165, v165
	v_pk_mul_f32 v[194:195], v[108:109], v[216:217] op_sel_hi:[1,0]
	v_pk_mul_f32 v[196:197], v[110:111], v[216:217] op_sel_hi:[1,0]
	v_pk_mul_f32 v[198:199], v[96:97], v[216:217] op_sel_hi:[1,0]
	v_pk_mul_f32 v[200:201], v[98:99], v[216:217] op_sel_hi:[1,0]
	v_pk_mul_f32 v[100:101], v[96:97], v[100:101]
	v_exp_f32_e32 v194, v194
	v_exp_f32_e32 v195, v195
	v_exp_f32_e32 v196, v196
	v_exp_f32_e32 v197, v197
	v_exp_f32_e32 v198, v198
	v_exp_f32_e32 v199, v199
	v_exp_f32_e32 v200, v200
	v_exp_f32_e32 v201, v201
	v_pk_add_f32 v[194:195], v[194:195], 1.0 op_sel_hi:[1,0]
	v_pk_add_f32 v[196:197], v[196:197], 1.0 op_sel_hi:[1,0]
	v_pk_add_f32 v[198:199], v[198:199], 1.0 op_sel_hi:[1,0]
	v_pk_add_f32 v[200:201], v[200:201], 1.0 op_sel_hi:[1,0]
	v_rcp_f32_e32 v194, v194
	v_rcp_f32_e32 v195, v195
	v_rcp_f32_e32 v196, v196
	v_rcp_f32_e32 v197, v197
	v_rcp_f32_e32 v198, v198
	v_rcp_f32_e32 v199, v199
	v_rcp_f32_e32 v200, v200
	v_rcp_f32_e32 v201, v201
	v_pk_mul_f32 v[194:195], v[218:219], v[194:195] op_sel_hi:[0,1]
	v_pk_mul_f32 v[196:197], v[218:219], v[196:197] op_sel_hi:[0,1]
	v_pk_mul_f32 v[198:199], v[218:219], v[198:199] op_sel_hi:[0,1]
	v_pk_mul_f32 v[200:201], v[218:219], v[200:201] op_sel_hi:[0,1]
	v_pk_mul_f32 v[104:105], v[104:105], v[194:195]
	v_pk_mul_f32 v[106:107], v[106:107], v[196:197]
	v_pk_mul_f32 v[100:101], v[100:101], v[198:199]
	v_pk_mul_f32 v[102:103], v[102:103], v[200:201]
	v_mad_i64_i32 v[230:231], s[6:7], v176, s25, v[224:225]
	v_cvt_pk_bf16_f32 v104, v104, v105
	v_cvt_pk_bf16_f32 v105, v106, v107
	v_cvt_pk_bf16_f32 v106, v100, v101
	v_cvt_pk_bf16_f32 v107, v102, v103
	v_lshl_add_u64 v[230:231], v[230:231], 0, v[226:227]
	global_store_dwordx4 v[230:231], v[104:107], off nt
	v_mul_f32_e32 v216, 0xbfb8aa3b, v145
	v_mul_f32_e32 v218, v145, v145
	v_pk_mul_f32 v[194:195], v[92:93], v[216:217] op_sel_hi:[1,0]
	v_pk_mul_f32 v[196:197], v[94:95], v[216:217] op_sel_hi:[1,0]
; __device__ __forceinline__ unsigned cvt_pk_bf16(float lo, float hi) { unsigned r; asm volatile("v_cvt_pk_bf16_f32 %0, %1, %2" : "=v"(r) : "v"(lo), "v"(hi)); return r; }
;     __device__ __forceinline__ void operator()(const f32x4 (&acc)[2][2][4][2], const Unit& u, int wr, int wc, int fr, int fq) const {
;     ...
;             for (int m = 0; m < 4; ++m) { const int row = row0 + ai * HALF + m * 16; const float rs = rsv[ai][m], c1 = rs * -1.4426950408889634f, rs2 = rs * rs;
;                 u32x4 w;
; #pragma unroll
;                 for (int n = 0; n < 2; ++n)
; #pragma unroll
;                     for (int h = 0; h < 2; ++h) { const f32x2 g = (f32x2){acc[ai][0][m][n][2 * h], acc[ai][0][m][n][2 * h + 1]}, up = (f32x2){acc[ai][1][m][n][2 * h], acc[ai][1][m][n][2 * h + 1]};
;                         const f32x2 t = g * c1; f32x2 d = (f32x2){__builtin_amdgcn_exp2f(t[0]), __builtin_amdgcn_exp2f(t[1])} + 1.0f;
;                         const f32x2 r = (f32x2){__builtin_amdgcn_rcpf(d[0]), __builtin_amdgcn_rcpf(d[1])}; const f32x2 o = (g * up) * (r * rs2);
;                         w[2 * n + h] = cvt_pk_bf16(o[0], o[1]); }
;                 __builtin_nontemporal_store(w, (u32x4*)(H + (size_t)row * ldh + col0)); }
	v_pk_mul_f32 v[198:199], v[80:81], v[216:217] op_sel_hi:[1,0]
	v_pk_mul_f32 v[200:201], v[82:83], v[216:217] op_sel_hi:[1,0]
	v_pk_mul_f32 v[84:85], v[80:81], v[84:85]
	v_exp_f32_e32 v194, v194
	v_exp_f32_e32 v195, v195
	v_exp_f32_e32 v196, v196
	v_exp_f32_e32 v197, v197
	v_exp_f32_e32 v198, v198
	v_exp_f32_e32 v199, v199
	v_exp_f32_e32 v200, v200
	v_exp_f32_e32 v201, v201
	v_pk_add_f32 v[194:195], v[194:195], 1.0 op_sel_hi:[1,0]
	v_pk_add_f32 v[196:197], v[196:197], 1.0 op_sel_hi:[1,0]
	v_pk_add_f32 v[198:199], v[198:199], 1.0 op_sel_hi:[1,0]
	v_pk_add_f32 v[200:201], v[200:201], 1.0 op_sel_hi:[1,0]
	v_rcp_f32_e32 v194, v194
	v_rcp_f32_e32 v195, v195
	v_rcp_f32_e32 v196, v196
	v_rcp_f32_e32 v197, v197
	v_rcp_f32_e32 v198, v198
	v_rcp_f32_e32 v199, v199
	v_rcp_f32_e32 v200, v200
	v_rcp_f32_e32 v201, v201
	v_pk_mul_f32 v[194:195], v[218:219], v[194:195] op_sel_hi:[0,1]
	v_pk_mul_f32 v[196:197], v[218:219], v[196:197] op_sel_hi:[0,1]
	v_pk_mul_f32 v[198:199], v[218:219], v[198:199] op_sel_hi:[0,1]
	v_pk_mul_f32 v[200:201], v[218:219], v[200:201] op_sel_hi:[0,1]
	v_pk_mul_f32 v[88:89], v[88:89], v[194:195]
	v_pk_mul_f32 v[90:91], v[90:91], v[196:197]
	v_pk_mul_f32 v[84:85], v[84:85], v[198:199]
	v_pk_mul_f32 v[86:87], v[86:87], v[200:201]
	v_mad_i64_i32 v[230:231], s[6:7], v174, s25, v[224:225]
	v_cvt_pk_bf16_f32 v88, v88, v89
	v_cvt_pk_bf16_f32 v89, v90, v91
	v_cvt_pk_bf16_f32 v90, v84, v85
	v_cvt_pk_bf16_f32 v91, v86, v87
	v_lshl_add_u64 v[230:231], v[230:231], 0, v[226:227]
	global_store_dwordx4 v[230:231], v[88:91], off nt
	v_mul_f32_e32 v216, 0xbfb8aa3b, v144
	v_mul_f32_e32 v218, v144, v144
	v_pk_mul_f32 v[194:195], v[76:77], v[216:217] op_sel_hi:[1,0]
	v_pk_mul_f32 v[196:197], v[78:79], v[216:217] op_sel_hi:[1,0]
	v_pk_mul_f32 v[198:199], v[64:65], v[216:217] op_sel_hi:[1,0]
	v_pk_mul_f32 v[200:201], v[66:67], v[216:217] op_sel_hi:[1,0]
	v_pk_mul_f32 v[68:69], v[64:65], v[68:69]
	v_exp_f32_e32 v194, v194
	v_exp_f32_e32 v195, v195
	v_exp_f32_e32 v196, v196
	v_exp_f32_e32 v197, v197
	v_exp_f32_e32 v198, v198
	v_exp_f32_e32 v199, v199
	v_exp_f32_e32 v200, v200
	v_exp_f32_e32 v201, v201
	v_pk_add_f32 v[194:195], v[194:195], 1.0 op_sel_hi:[1,0]
	v_pk_add_f32 v[196:197], v[196:197], 1.0 op_sel_hi:[1,0]
	v_pk_add_f32 v[198:199], v[198:199], 1.0 op_sel_hi:[1,0]
	v_pk_add_f32 v[200:201], v[200:201], 1.0 op_sel_hi:[1,0]
	v_rcp_f32_e32 v194, v194
	v_rcp_f32_e32 v195, v195
	v_rcp_f32_e32 v196, v196
	v_rcp_f32_e32 v197, v197
	v_rcp_f32_e32 v198, v198
	v_rcp_f32_e32 v199, v199
	v_rcp_f32_e32 v200, v200
	v_rcp_f32_e32 v201, v201
	v_pk_mul_f32 v[194:195], v[218:219], v[194:195] op_sel_hi:[0,1]
	v_pk_mul_f32 v[196:197], v[218:219], v[196:197] op_sel_hi:[0,1]
	v_pk_mul_f32 v[198:199], v[218:219], v[198:199] op_sel_hi:[0,1]
	v_pk_mul_f32 v[200:201], v[218:219], v[200:201] op_sel_hi:[0,1]
	v_pk_mul_f32 v[72:73], v[72:73], v[194:195]
	v_pk_mul_f32 v[74:75], v[74:75], v[196:197]
	v_pk_mul_f32 v[68:69], v[68:69], v[198:199]
	v_pk_mul_f32 v[70:71], v[70:71], v[200:201]
	v_mad_i64_i32 v[230:231], s[6:7], v172, s25, v[224:225]
	v_cvt_pk_bf16_f32 v72, v72, v73
	v_cvt_pk_bf16_f32 v73, v74, v75
	v_cvt_pk_bf16_f32 v74, v68, v69
	v_cvt_pk_bf16_f32 v75, v70, v71
	v_lshl_add_u64 v[230:231], v[230:231], 0, v[226:227]
	global_store_dwordx4 v[230:231], v[72:75], off nt
	v_mul_f32_e32 v216, 0xbfb8aa3b, v137
	v_mul_f32_e32 v218, v137, v137
	v_pk_mul_f32 v[194:195], v[60:61], v[216:217] op_sel_hi:[1,0]
	v_pk_mul_f32 v[196:197], v[62:63], v[216:217] op_sel_hi:[1,0]
	v_pk_mul_f32 v[198:199], v[48:49], v[216:217] op_sel_hi:[1,0]
	v_pk_mul_f32 v[200:201], v[50:51], v[216:217] op_sel_hi:[1,0]
	v_pk_mul_f32 v[52:53], v[48:49], v[52:53]
	v_exp_f32_e32 v194, v194
	v_exp_f32_e32 v195, v195
	v_exp_f32_e32 v196, v196
	v_exp_f32_e32 v197, v197
	v_exp_f32_e32 v198, v198
	v_exp_f32_e32 v199, v199
	v_exp_f32_e32 v200, v200
	v_exp_f32_e32 v201, v201
	v_pk_add_f32 v[194:195], v[194:195], 1.0 op_sel_hi:[1,0]
	v_pk_add_f32 v[196:197], v[196:197], 1.0 op_sel_hi:[1,0]
	v_pk_add_f32 v[198:199], v[198:199], 1.0 op_sel_hi:[1,0]
	v_pk_add_f32 v[200:201], v[200:201], 1.0 op_sel_hi:[1,0]
	v_rcp_f32_e32 v194, v194
	v_rcp_f32_e32 v195, v195
	v_rcp_f32_e32 v196, v196
	v_rcp_f32_e32 v197, v197
	v_rcp_f32_e32 v198, v198
	v_rcp_f32_e32 v199, v199
	v_rcp_f32_e32 v200, v200
	v_rcp_f32_e32 v201, v201
	v_pk_mul_f32 v[194:195], v[218:219], v[194:195] op_sel_hi:[0,1]
	v_pk_mul_f32 v[196:197], v[218:219], v[196:197] op_sel_hi:[0,1]
	v_pk_mul_f32 v[198:199], v[218:219], v[198:199] op_sel_hi:[0,1]
	v_pk_mul_f32 v[200:201], v[218:219], v[200:201] op_sel_hi:[0,1]
	v_pk_mul_f32 v[56:57], v[56:57], v[194:195]
	v_pk_mul_f32 v[58:59], v[58:59], v[196:197]
	v_pk_mul_f32 v[52:53], v[52:53], v[198:199]
	v_pk_mul_f32 v[54:55], v[54:55], v[200:201]
	v_mad_i64_i32 v[230:231], s[6:7], v170, s25, v[224:225]
	v_cvt_pk_bf16_f32 v56, v56, v57
	v_cvt_pk_bf16_f32 v57, v58, v59
	v_cvt_pk_bf16_f32 v58, v52, v53
	v_cvt_pk_bf16_f32 v59, v54, v55
	v_lshl_add_u64 v[230:231], v[230:231], 0, v[226:227]
	global_store_dwordx4 v[230:231], v[56:59], off nt
	v_mul_f32_e32 v216, 0xbfb8aa3b, v136
	v_mul_f32_e32 v218, v136, v136
	v_pk_mul_f32 v[194:195], v[44:45], v[216:217] op_sel_hi:[1,0]
; __device__ __forceinline__ unsigned cvt_pk_bf16(float lo, float hi) { unsigned r; asm volatile("v_cvt_pk_bf16_f32 %0, %1, %2" : "=v"(r) : "v"(lo), "v"(hi)); return r; }
; #define PG8_BAR __builtin_amdgcn_s_barrier()
;     __device__ __forceinline__ void operator()(const f32x4 (&acc)[2][2][4][2], const Unit& u, int wr, int wc, int fr, int fq) const {
;     ...
;             for (int m = 0; m < 4; ++m) { const int row = row0 + ai * HALF + m * 16; const float rs = rsv[ai][m], c1 = rs * -1.4426950408889634f, rs2 = rs * rs;
;                 u32x4 w;
; #pragma unroll
;                 for (int n = 0; n < 2; ++n)
; #pragma unroll
;                     for (int h = 0; h < 2; ++h) { const f32x2 g = (f32x2){acc[ai][0][m][n][2 * h], acc[ai][0][m][n][2 * h + 1]}, up = (f32x2){acc[ai][1][m][n][2 * h], acc[ai][1][m][n][2 * h + 1]};
;                         const f32x2 t = g * c1; f32x2 d = (f32x2){__builtin_amdgcn_exp2f(t[0]), __builtin_amdgcn_exp2f(t[1])} + 1.0f;
;                         const f32x2 r = (f32x2){__builtin_amdgcn_rcpf(d[0]), __builtin_amdgcn_rcpf(d[1])}; const f32x2 o = (g * up) * (r * rs2);
;                         w[2 * n + h] = cvt_pk_bf16(o[0], o[1]); }
;                 __builtin_nontemporal_store(w, (u32x4*)(H + (size_t)row * ldh + col0)); }
; template <class Epi, class Sched, bool ALIGN_EPI = false, bool SP2 = false>
; __device__ __forceinline__ void gemm_phase(PG8_LAS unsigned char* lds, const Gemm g, const Sched& S, const Epi& E) {
;     ...
;         if constexpr (ALIGN_EPI) { if (wr == 1) PG8_BAR; }
	v_pk_mul_f32 v[196:197], v[46:47], v[216:217] op_sel_hi:[1,0]
	v_pk_mul_f32 v[198:199], v[32:33], v[216:217] op_sel_hi:[1,0]
	v_pk_mul_f32 v[200:201], v[34:35], v[216:217] op_sel_hi:[1,0]
	v_pk_mul_f32 v[36:37], v[32:33], v[36:37]
	v_exp_f32_e32 v194, v194
	v_exp_f32_e32 v195, v195
	v_exp_f32_e32 v196, v196
	v_exp_f32_e32 v197, v197
	v_exp_f32_e32 v198, v198
	v_exp_f32_e32 v199, v199
	v_exp_f32_e32 v200, v200
	v_exp_f32_e32 v201, v201
	v_pk_add_f32 v[194:195], v[194:195], 1.0 op_sel_hi:[1,0]
	v_pk_add_f32 v[196:197], v[196:197], 1.0 op_sel_hi:[1,0]
	v_pk_add_f32 v[198:199], v[198:199], 1.0 op_sel_hi:[1,0]
	v_pk_add_f32 v[200:201], v[200:201], 1.0 op_sel_hi:[1,0]
	v_rcp_f32_e32 v194, v194
	v_rcp_f32_e32 v195, v195
	v_rcp_f32_e32 v196, v196
	v_rcp_f32_e32 v197, v197
	v_rcp_f32_e32 v198, v198
	v_rcp_f32_e32 v199, v199
	v_rcp_f32_e32 v200, v200
	v_rcp_f32_e32 v201, v201
	v_pk_mul_f32 v[194:195], v[218:219], v[194:195] op_sel_hi:[0,1]
	v_pk_mul_f32 v[196:197], v[218:219], v[196:197] op_sel_hi:[0,1]
	v_pk_mul_f32 v[198:199], v[218:219], v[198:199] op_sel_hi:[0,1]
	v_pk_mul_f32 v[200:201], v[218:219], v[200:201] op_sel_hi:[0,1]
	v_pk_mul_f32 v[40:41], v[40:41], v[194:195]
	v_pk_mul_f32 v[42:43], v[42:43], v[196:197]
	v_pk_mul_f32 v[36:37], v[36:37], v[198:199]
	v_pk_mul_f32 v[38:39], v[38:39], v[200:201]
	v_mad_i64_i32 v[230:231], s[6:7], v168, s25, v[224:225]
	v_cvt_pk_bf16_f32 v40, v40, v41
	v_cvt_pk_bf16_f32 v41, v42, v43
	v_cvt_pk_bf16_f32 v42, v36, v37
	v_cvt_pk_bf16_f32 v43, v38, v39
	v_lshl_add_u64 v[230:231], v[230:231], 0, v[226:227]
	global_store_dwordx4 v[230:231], v[40:43], off nt
	v_mul_f32_e32 v216, 0xbfb8aa3b, v129
	v_mul_f32_e32 v218, v129, v129
	v_pk_mul_f32 v[194:195], v[28:29], v[216:217] op_sel_hi:[1,0]
	v_pk_mul_f32 v[196:197], v[30:31], v[216:217] op_sel_hi:[1,0]
	v_pk_mul_f32 v[198:199], v[16:17], v[216:217] op_sel_hi:[1,0]
	v_pk_mul_f32 v[200:201], v[18:19], v[216:217] op_sel_hi:[1,0]
	v_pk_mul_f32 v[20:21], v[16:17], v[20:21]
	v_exp_f32_e32 v194, v194
	v_exp_f32_e32 v195, v195
	v_exp_f32_e32 v196, v196
	v_exp_f32_e32 v197, v197
	v_exp_f32_e32 v198, v198
	v_exp_f32_e32 v199, v199
	v_exp_f32_e32 v200, v200
	v_exp_f32_e32 v201, v201
	v_pk_add_f32 v[194:195], v[194:195], 1.0 op_sel_hi:[1,0]
	v_pk_add_f32 v[196:197], v[196:197], 1.0 op_sel_hi:[1,0]
	v_pk_add_f32 v[198:199], v[198:199], 1.0 op_sel_hi:[1,0]
	v_pk_add_f32 v[200:201], v[200:201], 1.0 op_sel_hi:[1,0]
	v_rcp_f32_e32 v194, v194
	v_rcp_f32_e32 v195, v195
	v_rcp_f32_e32 v196, v196
	v_rcp_f32_e32 v197, v197
	v_rcp_f32_e32 v198, v198
	v_rcp_f32_e32 v199, v199
	v_rcp_f32_e32 v200, v200
	v_rcp_f32_e32 v201, v201
	v_pk_mul_f32 v[194:195], v[218:219], v[194:195] op_sel_hi:[0,1]
	v_pk_mul_f32 v[196:197], v[218:219], v[196:197] op_sel_hi:[0,1]
	v_pk_mul_f32 v[198:199], v[218:219], v[198:199] op_sel_hi:[0,1]
	v_pk_mul_f32 v[200:201], v[218:219], v[200:201] op_sel_hi:[0,1]
	v_pk_mul_f32 v[24:25], v[24:25], v[194:195]
	v_pk_mul_f32 v[26:27], v[26:27], v[196:197]
	v_pk_mul_f32 v[20:21], v[20:21], v[198:199]
	v_pk_mul_f32 v[22:23], v[22:23], v[200:201]
	v_mad_i64_i32 v[230:231], s[6:7], v166, s25, v[224:225]
	v_cvt_pk_bf16_f32 v24, v24, v25
	v_cvt_pk_bf16_f32 v25, v26, v27
	v_cvt_pk_bf16_f32 v26, v20, v21
	v_cvt_pk_bf16_f32 v27, v22, v23
	v_lshl_add_u64 v[230:231], v[230:231], 0, v[226:227]
	global_store_dwordx4 v[230:231], v[24:27], off nt
	v_mul_f32_e32 v216, 0xbfb8aa3b, v128
	v_mul_f32_e32 v218, v128, v128
	v_pk_mul_f32 v[194:195], v[12:13], v[216:217] op_sel_hi:[1,0]
	v_pk_mul_f32 v[196:197], v[14:15], v[216:217] op_sel_hi:[1,0]
	v_pk_mul_f32 v[198:199], v[4:5], v[216:217] op_sel_hi:[1,0]
	v_pk_mul_f32 v[200:201], v[6:7], v[216:217] op_sel_hi:[1,0]
	v_exp_f32_e32 v194, v194
	v_exp_f32_e32 v195, v195
	v_exp_f32_e32 v196, v196
	v_exp_f32_e32 v197, v197
	v_exp_f32_e32 v198, v198
	v_exp_f32_e32 v199, v199
	v_exp_f32_e32 v200, v200
	v_exp_f32_e32 v201, v201
	v_pk_add_f32 v[194:195], v[194:195], 1.0 op_sel_hi:[1,0]
	v_pk_add_f32 v[196:197], v[196:197], 1.0 op_sel_hi:[1,0]
	v_pk_add_f32 v[198:199], v[198:199], 1.0 op_sel_hi:[1,0]
	v_pk_add_f32 v[200:201], v[200:201], 1.0 op_sel_hi:[1,0]
	v_rcp_f32_e32 v194, v194
	v_rcp_f32_e32 v195, v195
	v_rcp_f32_e32 v196, v196
	v_rcp_f32_e32 v197, v197
	v_rcp_f32_e32 v198, v198
	v_rcp_f32_e32 v199, v199
	v_rcp_f32_e32 v200, v200
	v_rcp_f32_e32 v201, v201
	v_pk_mul_f32 v[194:195], v[218:219], v[194:195] op_sel_hi:[0,1]
	v_pk_mul_f32 v[196:197], v[218:219], v[196:197] op_sel_hi:[0,1]
	v_pk_mul_f32 v[198:199], v[218:219], v[198:199] op_sel_hi:[0,1]
	v_pk_mul_f32 v[200:201], v[218:219], v[200:201] op_sel_hi:[0,1]
	v_pk_mul_f32 v[8:9], v[8:9], v[194:195]
	v_pk_mul_f32 v[10:11], v[10:11], v[196:197]
	v_pk_mul_f32 v[0:1], v[0:1], v[198:199]
	v_pk_mul_f32 v[2:3], v[2:3], v[200:201]
	v_mad_i64_i32 v[230:231], s[6:7], v164, s25, v[224:225]
	v_cvt_pk_bf16_f32 v8, v8, v9
	v_cvt_pk_bf16_f32 v9, v10, v11
	v_cvt_pk_bf16_f32 v10, v0, v1
	v_cvt_pk_bf16_f32 v11, v2, v3
	v_lshl_add_u64 v[230:231], v[230:231], 0, v[226:227]
	s_mov_b64 s[6:7], -1
	global_store_dwordx4 v[230:231], v[8:11], off nt
	s_cbranch_vccnz .LBB0_194
	s_andn2_b64 vcc, exec, s[8:9]
	s_cbranch_vccnz .LBB0_193
	s_mov_b32 s96, 1
	s_branch .LBB0_193
